# same wait relaxation also in the out-projection and MLP-down GEMMs
# speedup vs baseline: 1.0046x; 1.0015x over previous
.LBB0_732:
	s_add_u32 s8, s70, 0x4000000
	s_addc_u32 s9, s71, 0
	s_add_u32 s14, s72, 0x4860000
	s_addc_u32 s15, s73, 0
	s_lshl_b32 s5, s5, 5
	s_mov_b64 s[16:17], 0x80
	s_and_b32 s22, s5, 0x60
	s_add_i32 m0, s37, 0x18000
	v_lshl_add_u64 v[6:7], v[6:7], 0, s[16:17]
	s_lshl_b32 s19, s4, 13
	s_lshl_b32 s5, s22, 7
	s_waitcnt vmcnt(2)
	s_barrier
	global_load_lds_dwordx4 v[6:7], off
	v_lshl_add_u64 v[4:5], v[4:5], 0, s[16:17]
	s_add_i32 m0, s37, 0x1a000
	s_add_i32 s53, s37, 0x8000
	s_add_i32 s54, s37, 0xa000
	global_load_lds_dwordx4 v[4:5], off
	v_lshl_add_u64 v[0:1], v[0:1], 0, s[16:17]
	s_mov_b32 m0, s53
	s_add_u32 s20, s40, 0x40080
	global_load_lds_dwordx4 v[0:1], off
	v_lshl_add_u64 v[0:1], v[2:3], 0, s[16:17]
	s_mov_b32 m0, s54
	s_addc_u32 s21, s41, 0
	global_load_lds_dwordx4 v[0:1], off
	s_add_i32 m0, s37, 0x1c000
	v_lshl_add_u64 v[0:1], s[20:21], 0, v[154:155]
	global_load_lds_dwordx4 v[0:1], off
	v_lshl_add_u64 v[0:1], s[20:21], 0, v[158:159]
	s_add_i32 m0, s37, 0x1e000
	v_lshlrev_b32_e32 v3, 2, v192
	global_load_lds_dwordx4 v[0:1], off
	v_bfe_u32 v0, v192, 4, 2
	v_and_b32_e32 v1, 15, v192
	v_lshl_or_b32 v184, s4, 6, v1
	v_lshlrev_b32_e32 v2, 4, v0
	v_lshlrev_b32_e32 v4, 6, v192
	s_movk_i32 s4, 0x3c0
	v_lshl_or_b32 v1, v1, 6, v2
	v_and_b32_e32 v3, 32, v3
	v_and_or_b32 v2, v4, s4, v2
	v_bitop3_b32 v185, s5, v2, v3 bitop3:0xf6
	v_cmp_eq_u32_e64 s[4:5], 0, v0
	v_lshl_or_b32 v186, v0, 3, s22
	v_lshlrev_b32_e32 v0, 8, v192
	v_and_b32_e32 v0, 0x38000, v0
	v_lshlrev_b32_e32 v2, 11, v10
	v_or3_b32 v0, v8, v0, v2
	v_add_u32_e32 v160, v0, v9
	v_lshlrev_b32_e32 v0, 4, v11
	v_and_b32_e32 v0, 0x78000, v0
	s_waitcnt vmcnt(6)
	s_cmpk_lt_u32 s18, 0x100
	v_or3_b32 v0, v8, v0, v2
	v_bitop3_b32 v1, v1, s19, v3 bitop3:0xde
	s_cselect_b64 s[18:19], -1, 0
	v_add_u32_e32 v162, v0, v9
	s_add_i32 s58, 0, 0x10000
	s_add_i32 s59, 0, 0x14000
	v_mbcnt_lo_u32_b32 v0, -1, 0
	s_ashr_i32 s55, s34, 31
	s_mov_b32 s56, s34
	s_ashr_i32 s57, s2, 31
	v_mov_b32_e32 v161, v155
	v_mov_b32_e32 v163, v155
	v_add_u32_e32 v187, s58, v185
	v_add_u32_e32 v188, s59, v185
	v_add_u32_e32 v189, 0, v1
	v_mbcnt_hi_u32_b32 v190, -1, v0
	v_mov_b64_e32 v[164:165], 0x1ff
	s_barrier
	s_waitcnt vmcnt(0)
	s_branch .LBB0_735

.LBB0_742:
	s_ashr_i32 s23, s22, 31
	s_lshl_b64 s[26:27], s[22:23], 19
	s_add_u32 s26, s44, s26
	s_addc_u32 s27, s45, s27
	s_and_b64 s[28:29], s[24:25], exec
	s_cselect_b32 s23, s27, s39
	s_cselect_b32 s31, s26, s38
	s_ashr_i32 s21, s20, 31
	s_lshl_b64 s[28:29], s[20:21], 19
	s_add_u32 s28, s46, s28
	s_addc_u32 s29, s47, s29
	s_and_b64 s[42:43], s[24:25], exec
	s_cselect_b32 s21, s29, s41
	s_cselect_b32 s60, s28, s40
	s_add_u32 s38, s38, 0x40080
	s_addc_u32 s39, s39, 0
	s_add_u32 s61, s40, 0x100
	v_mov_b32_e32 v0, 0
	s_addc_u32 s62, s41, 0
	s_mov_b32 s63, -2
	s_waitcnt lgkmcnt(0)
	v_mov_b32_e32 v1, v0
	v_mov_b32_e32 v2, v0
	v_mov_b32_e32 v3, v0
	v_mov_b32_e32 v4, v0
	v_mov_b32_e32 v5, v0
	v_mov_b32_e32 v6, v0
	v_mov_b32_e32 v7, v0
	v_mov_b32_e32 v16, v0
	v_mov_b32_e32 v17, v0
	v_mov_b32_e32 v18, v0
	v_mov_b32_e32 v19, v0
	v_mov_b32_e32 v20, v0
	v_mov_b32_e32 v21, v0
	v_mov_b32_e32 v22, v0
	v_mov_b32_e32 v23, v0
	v_mov_b32_e32 v32, v0
	v_mov_b32_e32 v33, v0
	v_mov_b32_e32 v34, v0
	v_mov_b32_e32 v35, v0
	v_mov_b32_e32 v36, v0
	v_mov_b32_e32 v37, v0
	v_mov_b32_e32 v38, v0
	v_mov_b32_e32 v39, v0
	v_mov_b32_e32 v48, v0
	v_mov_b32_e32 v49, v0
	v_mov_b32_e32 v50, v0
	v_mov_b32_e32 v51, v0
	v_mov_b32_e32 v52, v0
	v_mov_b32_e32 v53, v0
	v_mov_b32_e32 v54, v0
	v_mov_b32_e32 v55, v0
	v_mov_b32_e32 v8, v0
	v_mov_b32_e32 v9, v0
	v_mov_b32_e32 v10, v0
	v_mov_b32_e32 v11, v0
	v_mov_b32_e32 v12, v0
	v_mov_b32_e32 v13, v0
	v_mov_b32_e32 v14, v0
	v_mov_b32_e32 v15, v0
	v_mov_b32_e32 v24, v0
	v_mov_b32_e32 v25, v0
	v_mov_b32_e32 v26, v0
	v_mov_b32_e32 v27, v0
	v_mov_b32_e32 v28, v0
	v_mov_b32_e32 v29, v0
	v_mov_b32_e32 v30, v0
	v_mov_b32_e32 v31, v0
	v_mov_b32_e32 v40, v0
	v_mov_b32_e32 v41, v0
	v_mov_b32_e32 v42, v0
	v_mov_b32_e32 v43, v0
	v_mov_b32_e32 v44, v0
	v_mov_b32_e32 v45, v0
	v_mov_b32_e32 v46, v0
	v_mov_b32_e32 v47, v0
	v_mov_b32_e32 v56, v0
	v_mov_b32_e32 v57, v0
	v_mov_b32_e32 v58, v0
	v_mov_b32_e32 v59, v0
	v_mov_b32_e32 v60, v0
	v_mov_b32_e32 v61, v0
	v_mov_b32_e32 v62, v0
	v_mov_b32_e32 v63, v0
	v_mov_b32_e32 v64, v0
	v_mov_b32_e32 v65, v0
	v_mov_b32_e32 v66, v0
	v_mov_b32_e32 v67, v0
	v_mov_b32_e32 v68, v0
	v_mov_b32_e32 v69, v0
	v_mov_b32_e32 v70, v0
	v_mov_b32_e32 v71, v0
	v_mov_b32_e32 v80, v0
	v_mov_b32_e32 v81, v0
	v_mov_b32_e32 v82, v0
	v_mov_b32_e32 v83, v0
	v_mov_b32_e32 v84, v0
	v_mov_b32_e32 v85, v0
	v_mov_b32_e32 v86, v0
	v_mov_b32_e32 v87, v0
	v_mov_b32_e32 v96, v0
	v_mov_b32_e32 v97, v0
	v_mov_b32_e32 v98, v0
	v_mov_b32_e32 v99, v0
	v_mov_b32_e32 v100, v0
	v_mov_b32_e32 v101, v0
	v_mov_b32_e32 v102, v0
	v_mov_b32_e32 v103, v0
	v_mov_b32_e32 v112, v0
	v_mov_b32_e32 v113, v0
	v_mov_b32_e32 v114, v0
	v_mov_b32_e32 v115, v0
	v_mov_b32_e32 v116, v0
	v_mov_b32_e32 v117, v0
	v_mov_b32_e32 v118, v0
	v_mov_b32_e32 v119, v0
	v_mov_b32_e32 v72, v0
	v_mov_b32_e32 v73, v0
	v_mov_b32_e32 v74, v0
	v_mov_b32_e32 v75, v0
	v_mov_b32_e32 v76, v0
	v_mov_b32_e32 v77, v0
	v_mov_b32_e32 v78, v0
	v_mov_b32_e32 v79, v0
	v_mov_b32_e32 v88, v0
	v_mov_b32_e32 v89, v0
	v_mov_b32_e32 v90, v0
	v_mov_b32_e32 v91, v0
	v_mov_b32_e32 v92, v0
	v_mov_b32_e32 v93, v0
	v_mov_b32_e32 v94, v0
	v_mov_b32_e32 v95, v0
	v_mov_b32_e32 v104, v0
	v_mov_b32_e32 v105, v0
	v_mov_b32_e32 v106, v0
	v_mov_b32_e32 v107, v0
	v_mov_b32_e32 v108, v0
	v_mov_b32_e32 v109, v0
	v_mov_b32_e32 v110, v0
	v_mov_b32_e32 v111, v0
	v_mov_b32_e32 v120, v0
	v_mov_b32_e32 v121, v0
	v_mov_b32_e32 v122, v0
	v_mov_b32_e32 v123, v0
	v_mov_b32_e32 v124, v0
	v_mov_b32_e32 v125, v0
	v_mov_b32_e32 v126, v0
	v_mov_b32_e32 v127, v0
.LBB0_743:
	ds_read_b128 v[128:131], v187
	ds_read_b128 v[132:135], v187 offset:1024
	ds_read_b128 v[136:139], v187 offset:2048
	ds_read_b128 v[140:143], v187 offset:3072
	ds_read_b128 v[144:147], v188
	ds_read_b128 v[148:151], v188 offset:1024
	ds_read_b128 v[166:169], v188 offset:2048
	ds_read_b128 v[170:173], v188 offset:3072
	s_add_u32 s40, s38, 0xfffc0080
	s_addc_u32 s41, s39, -1
	s_cmp_eq_u32 s63, 12
	s_cselect_b32 s43, s23, s41
	s_cselect_b32 s42, s31, s40
	s_cselect_b32 s41, s21, s62
	s_cselect_b32 s40, s60, s61
	v_lshl_add_u64 v[182:183], s[38:39], 0, v[160:161]
	s_add_i32 m0, s37, 0xc000
	ds_read_b128 v[174:177], v189
	ds_read_b128 v[178:181], v189 offset:1024
	ds_read_b128 v[194:197], v189 offset:2048
	ds_read_b128 v[198:201], v189 offset:3072
	ds_read_b128 v[202:205], v189 offset:4096
	ds_read_b128 v[206:209], v189 offset:5120
	ds_read_b128 v[210:213], v189 offset:6144
	ds_read_b128 v[214:217], v189 offset:7168
	global_load_lds_dwordx4 v[182:183], off
	v_lshl_add_u64 v[182:183], s[38:39], 0, v[162:163]
	s_add_i32 m0, s37, 0xe000
	s_nop 0
	global_load_lds_dwordx4 v[182:183], off
	s_cmp_eq_i32 s63, -2
	s_cbranch_scc1 .Lrxa_0_0
	s_waitcnt vmcnt(8)
.Lrxa_0_0:
	s_waitcnt lgkmcnt(0)
	s_barrier
	s_waitcnt lgkmcnt(0)
	v_mfma_f32_16x16x32_bf16 v[124:127], v[128:131], v[174:177], v[124:127]
	v_mfma_f32_16x16x32_bf16 v[120:123], v[136:139], v[174:177], v[120:123]
	v_mfma_f32_16x16x32_bf16 v[108:111], v[128:131], v[194:197], v[108:111]
	v_mfma_f32_16x16x32_bf16 v[104:107], v[136:139], v[194:197], v[104:107]
	v_mfma_f32_16x16x32_bf16 v[92:95], v[128:131], v[202:205], v[92:95]
	v_mfma_f32_16x16x32_bf16 v[88:91], v[136:139], v[202:205], v[88:91]
	v_mfma_f32_16x16x32_bf16 v[76:79], v[128:131], v[210:213], v[76:79]
	v_mfma_f32_16x16x32_bf16 v[72:75], v[136:139], v[210:213], v[72:75]
	v_mfma_f32_16x16x32_bf16 v[124:127], v[132:135], v[178:181], v[124:127]
	v_mfma_f32_16x16x32_bf16 v[120:123], v[140:143], v[178:181], v[120:123]
	v_mfma_f32_16x16x32_bf16 v[108:111], v[132:135], v[198:201], v[108:111]
	v_mfma_f32_16x16x32_bf16 v[104:107], v[140:143], v[198:201], v[104:107]
	v_mfma_f32_16x16x32_bf16 v[92:95], v[132:135], v[206:209], v[92:95]
	v_mfma_f32_16x16x32_bf16 v[88:91], v[140:143], v[206:209], v[88:91]
	v_mfma_f32_16x16x32_bf16 v[76:79], v[132:135], v[214:217], v[76:79]
	v_mfma_f32_16x16x32_bf16 v[72:75], v[140:143], v[214:217], v[72:75]
	v_mfma_f32_16x16x32_bf16 v[116:119], v[144:147], v[174:177], v[116:119]
	v_mfma_f32_16x16x32_bf16 v[112:115], v[166:169], v[174:177], v[112:115]
	v_mfma_f32_16x16x32_bf16 v[100:103], v[144:147], v[194:197], v[100:103]
	v_mfma_f32_16x16x32_bf16 v[96:99], v[166:169], v[194:197], v[96:99]
	v_mfma_f32_16x16x32_bf16 v[84:87], v[144:147], v[202:205], v[84:87]
	v_mfma_f32_16x16x32_bf16 v[80:83], v[166:169], v[202:205], v[80:83]
	v_mfma_f32_16x16x32_bf16 v[68:71], v[144:147], v[210:213], v[68:71]
	v_mfma_f32_16x16x32_bf16 v[64:67], v[166:169], v[210:213], v[64:67]
	v_mfma_f32_16x16x32_bf16 v[116:119], v[148:151], v[178:181], v[116:119]
	v_mfma_f32_16x16x32_bf16 v[112:115], v[170:173], v[178:181], v[112:115]
	v_mfma_f32_16x16x32_bf16 v[100:103], v[148:151], v[198:201], v[100:103]
	v_mfma_f32_16x16x32_bf16 v[96:99], v[170:173], v[198:201], v[96:99]
	v_mfma_f32_16x16x32_bf16 v[84:87], v[148:151], v[206:209], v[84:87]
	v_mfma_f32_16x16x32_bf16 v[80:83], v[170:173], v[206:209], v[80:83]
	v_mfma_f32_16x16x32_bf16 v[68:71], v[148:151], v[214:217], v[68:71]
	v_mfma_f32_16x16x32_bf16 v[64:67], v[170:173], v[214:217], v[64:67]
	s_barrier
	s_add_i32 s64, s58, s48
	v_lshl_add_u64 v[182:183], s[40:41], 0, v[154:155]
	s_mov_b32 m0, s64
	ds_read_b128 v[174:177], v189 offset:16384
	ds_read_b128 v[178:181], v189 offset:17408
	ds_read_b128 v[194:197], v189 offset:18432
	ds_read_b128 v[198:201], v189 offset:19456
	ds_read_b128 v[202:205], v189 offset:20480
	ds_read_b128 v[206:209], v189 offset:21504
	ds_read_b128 v[210:213], v189 offset:22528
	ds_read_b128 v[214:217], v189 offset:23552
	global_load_lds_dwordx4 v[182:183], off
	s_add_i32 m0, s64, 0x2000
	s_add_u32 s64, s40, 0x40000
	v_lshl_add_u64 v[218:219], s[40:41], 0, v[158:159]
	s_addc_u32 s65, s41, 0
	s_add_i32 s66, s59, s48
	global_load_lds_dwordx4 v[218:219], off
	v_lshl_add_u64 v[220:221], s[64:65], 0, v[154:155]
	s_mov_b32 m0, s66
	v_lshl_add_u64 v[222:223], s[42:43], 0, v[156:157]
	global_load_lds_dwordx4 v[220:221], off
	v_lshl_add_u64 v[220:221], s[64:65], 0, v[158:159]
	s_add_i32 m0, s66, 0x2000
	s_nop 0
	global_load_lds_dwordx4 v[220:221], off
	v_lshl_add_u64 v[220:221], s[42:43], 0, v[152:153]
	s_mov_b32 m0, s37
	s_nop 0
	global_load_lds_dwordx4 v[220:221], off
	s_mov_b32 m0, s49
	s_nop 0
	global_load_lds_dwordx4 v[222:223], off
	s_cmp_eq_i32 s63, -2
	s_cbranch_scc1 .Lrxa_0_1
	s_waitcnt vmcnt(8)
.Lrxa_0_1:
	s_waitcnt lgkmcnt(0)
	s_barrier
	s_waitcnt lgkmcnt(0)
	v_mfma_f32_16x16x32_bf16 v[60:63], v[128:131], v[174:177], v[60:63]
	v_mfma_f32_16x16x32_bf16 v[56:59], v[136:139], v[174:177], v[56:59]
	v_mfma_f32_16x16x32_bf16 v[44:47], v[128:131], v[194:197], v[44:47]
	v_mfma_f32_16x16x32_bf16 v[40:43], v[136:139], v[194:197], v[40:43]
	v_mfma_f32_16x16x32_bf16 v[28:31], v[128:131], v[202:205], v[28:31]
	v_mfma_f32_16x16x32_bf16 v[24:27], v[136:139], v[202:205], v[24:27]
	v_mfma_f32_16x16x32_bf16 v[12:15], v[128:131], v[210:213], v[12:15]
	v_mfma_f32_16x16x32_bf16 v[8:11], v[136:139], v[210:213], v[8:11]
	v_mfma_f32_16x16x32_bf16 v[60:63], v[132:135], v[178:181], v[60:63]
	v_mfma_f32_16x16x32_bf16 v[56:59], v[140:143], v[178:181], v[56:59]
	v_mfma_f32_16x16x32_bf16 v[44:47], v[132:135], v[198:201], v[44:47]
	v_mfma_f32_16x16x32_bf16 v[40:43], v[140:143], v[198:201], v[40:43]
	v_mfma_f32_16x16x32_bf16 v[28:31], v[132:135], v[206:209], v[28:31]
	v_mfma_f32_16x16x32_bf16 v[24:27], v[140:143], v[206:209], v[24:27]
	v_mfma_f32_16x16x32_bf16 v[12:15], v[132:135], v[214:217], v[12:15]
	v_mfma_f32_16x16x32_bf16 v[8:11], v[140:143], v[214:217], v[8:11]
	v_mfma_f32_16x16x32_bf16 v[52:55], v[144:147], v[174:177], v[52:55]
	v_mfma_f32_16x16x32_bf16 v[48:51], v[166:169], v[174:177], v[48:51]
	v_mfma_f32_16x16x32_bf16 v[36:39], v[144:147], v[194:197], v[36:39]
	v_mfma_f32_16x16x32_bf16 v[32:35], v[166:169], v[194:197], v[32:35]
	v_mfma_f32_16x16x32_bf16 v[20:23], v[144:147], v[202:205], v[20:23]
	v_mfma_f32_16x16x32_bf16 v[16:19], v[166:169], v[202:205], v[16:19]
	v_mfma_f32_16x16x32_bf16 v[4:7], v[144:147], v[210:213], v[4:7]
	v_mfma_f32_16x16x32_bf16 v[0:3], v[166:169], v[210:213], v[0:3]
	v_mfma_f32_16x16x32_bf16 v[52:55], v[148:151], v[178:181], v[52:55]
	v_mfma_f32_16x16x32_bf16 v[48:51], v[170:173], v[178:181], v[48:51]
	v_mfma_f32_16x16x32_bf16 v[36:39], v[148:151], v[198:201], v[36:39]
	v_mfma_f32_16x16x32_bf16 v[32:35], v[170:173], v[198:201], v[32:35]
	v_mfma_f32_16x16x32_bf16 v[20:23], v[148:151], v[206:209], v[20:23]
	v_mfma_f32_16x16x32_bf16 v[16:19], v[170:173], v[206:209], v[16:19]
	v_mfma_f32_16x16x32_bf16 v[4:7], v[148:151], v[214:217], v[4:7]
	v_mfma_f32_16x16x32_bf16 v[0:3], v[170:173], v[214:217], v[0:3]
	s_barrier
	s_add_i32 s64, 0, 0x18000
	s_add_i32 s65, 0, 0x1c000
	v_add_u32_e32 v140, s64, v185
	v_add_u32_e32 v170, s65, v185
	ds_read_b128 v[128:131], v140
	ds_read_b128 v[132:135], v140 offset:1024
	ds_read_b128 v[136:139], v140 offset:2048
	ds_read_b128 v[140:143], v140 offset:3072
	ds_read_b128 v[144:147], v170
	ds_read_b128 v[148:151], v170 offset:1024
	ds_read_b128 v[166:169], v170 offset:2048
	ds_read_b128 v[170:173], v170 offset:3072
	s_add_u32 s42, s42, 0x40000
	s_addc_u32 s43, s43, 0
	s_mov_b32 m0, s50
	v_lshl_add_u64 v[224:225], s[42:43], 0, v[152:153]
	ds_read_b128 v[174:177], v189 offset:32768
	ds_read_b128 v[178:181], v189 offset:33792
	ds_read_b128 v[194:197], v189 offset:34816
	ds_read_b128 v[198:201], v189 offset:35840
	ds_read_b128 v[202:205], v189 offset:36864
	ds_read_b128 v[206:209], v189 offset:37888
	ds_read_b128 v[210:213], v189 offset:38912
	ds_read_b128 v[214:217], v189 offset:39936
	global_load_lds_dwordx4 v[224:225], off
	v_lshl_add_u64 v[224:225], s[42:43], 0, v[156:157]
	s_mov_b32 m0, s51
	s_nop 0
	global_load_lds_dwordx4 v[224:225], off
	s_waitcnt vmcnt(8)
	s_waitcnt lgkmcnt(0)
	s_barrier
	s_waitcnt lgkmcnt(0)
	v_mfma_f32_16x16x32_bf16 v[124:127], v[128:131], v[174:177], v[124:127]
	v_mfma_f32_16x16x32_bf16 v[120:123], v[136:139], v[174:177], v[120:123]
	v_mfma_f32_16x16x32_bf16 v[108:111], v[128:131], v[194:197], v[108:111]
	v_mfma_f32_16x16x32_bf16 v[104:107], v[136:139], v[194:197], v[104:107]
	v_mfma_f32_16x16x32_bf16 v[92:95], v[128:131], v[202:205], v[92:95]
	v_mfma_f32_16x16x32_bf16 v[88:91], v[136:139], v[202:205], v[88:91]
	v_mfma_f32_16x16x32_bf16 v[76:79], v[128:131], v[210:213], v[76:79]
	v_mfma_f32_16x16x32_bf16 v[72:75], v[136:139], v[210:213], v[72:75]
	v_mfma_f32_16x16x32_bf16 v[124:127], v[132:135], v[178:181], v[124:127]
	v_mfma_f32_16x16x32_bf16 v[120:123], v[140:143], v[178:181], v[120:123]
	v_mfma_f32_16x16x32_bf16 v[108:111], v[132:135], v[198:201], v[108:111]
	v_mfma_f32_16x16x32_bf16 v[104:107], v[140:143], v[198:201], v[104:107]
	v_mfma_f32_16x16x32_bf16 v[92:95], v[132:135], v[206:209], v[92:95]
	v_mfma_f32_16x16x32_bf16 v[88:91], v[140:143], v[206:209], v[88:91]
	v_mfma_f32_16x16x32_bf16 v[76:79], v[132:135], v[214:217], v[76:79]
	v_mfma_f32_16x16x32_bf16 v[72:75], v[140:143], v[214:217], v[72:75]
	v_mfma_f32_16x16x32_bf16 v[116:119], v[144:147], v[174:177], v[116:119]
	v_mfma_f32_16x16x32_bf16 v[112:115], v[166:169], v[174:177], v[112:115]
	v_mfma_f32_16x16x32_bf16 v[100:103], v[144:147], v[194:197], v[100:103]
	v_mfma_f32_16x16x32_bf16 v[96:99], v[166:169], v[194:197], v[96:99]
	v_mfma_f32_16x16x32_bf16 v[84:87], v[144:147], v[202:205], v[84:87]
	v_mfma_f32_16x16x32_bf16 v[80:83], v[166:169], v[202:205], v[80:83]
	v_mfma_f32_16x16x32_bf16 v[68:71], v[144:147], v[210:213], v[68:71]
	v_mfma_f32_16x16x32_bf16 v[64:67], v[166:169], v[210:213], v[64:67]
	v_mfma_f32_16x16x32_bf16 v[116:119], v[148:151], v[178:181], v[116:119]
	v_mfma_f32_16x16x32_bf16 v[112:115], v[170:173], v[178:181], v[112:115]
	v_mfma_f32_16x16x32_bf16 v[100:103], v[148:151], v[198:201], v[100:103]
	v_mfma_f32_16x16x32_bf16 v[96:99], v[170:173], v[198:201], v[96:99]
	v_mfma_f32_16x16x32_bf16 v[84:87], v[148:151], v[206:209], v[84:87]
	v_mfma_f32_16x16x32_bf16 v[80:83], v[170:173], v[206:209], v[80:83]
	v_mfma_f32_16x16x32_bf16 v[68:71], v[148:151], v[214:217], v[68:71]
	v_mfma_f32_16x16x32_bf16 v[64:67], v[170:173], v[214:217], v[64:67]
	s_barrier
	s_add_i32 s42, s64, s48
	v_lshl_add_u64 v[182:183], v[182:183], 0, s[16:17]
	s_mov_b32 m0, s42
	ds_read_b128 v[174:177], v189 offset:49152
	ds_read_b128 v[178:181], v189 offset:50176
	ds_read_b128 v[194:197], v189 offset:51200
	ds_read_b128 v[198:201], v189 offset:52224
	ds_read_b128 v[202:205], v189 offset:53248
	ds_read_b128 v[206:209], v189 offset:54272
	ds_read_b128 v[210:213], v189 offset:55296
	ds_read_b128 v[214:217], v189 offset:56320
	global_load_lds_dwordx4 v[182:183], off
	s_add_i32 m0, s42, 0x2000
	s_add_u32 s40, s40, 0x40080
	v_lshl_add_u64 v[182:183], v[218:219], 0, s[16:17]
	s_addc_u32 s41, s41, 0
	s_add_i32 s42, s65, s48
	global_load_lds_dwordx4 v[182:183], off
	v_lshl_add_u64 v[182:183], s[40:41], 0, v[154:155]
	s_mov_b32 m0, s42
	s_nop 0
	global_load_lds_dwordx4 v[182:183], off
	v_lshl_add_u64 v[182:183], s[40:41], 0, v[158:159]
	s_add_i32 m0, s42, 0x2000
	s_nop 0
	global_load_lds_dwordx4 v[182:183], off
	v_lshl_add_u64 v[182:183], v[220:221], 0, s[16:17]
	s_mov_b32 m0, s53
	s_nop 0
	global_load_lds_dwordx4 v[182:183], off
	v_lshl_add_u64 v[182:183], v[222:223], 0, s[16:17]
	s_mov_b32 m0, s54
	s_nop 0
	global_load_lds_dwordx4 v[182:183], off
	s_waitcnt vmcnt(8)
	s_waitcnt lgkmcnt(0)
	s_barrier
	s_waitcnt lgkmcnt(0)
	v_mfma_f32_16x16x32_bf16 v[60:63], v[128:131], v[174:177], v[60:63]
	v_mfma_f32_16x16x32_bf16 v[56:59], v[136:139], v[174:177], v[56:59]
	v_mfma_f32_16x16x32_bf16 v[44:47], v[128:131], v[194:197], v[44:47]
	v_mfma_f32_16x16x32_bf16 v[40:43], v[136:139], v[194:197], v[40:43]
	v_mfma_f32_16x16x32_bf16 v[28:31], v[128:131], v[202:205], v[28:31]
	v_mfma_f32_16x16x32_bf16 v[24:27], v[136:139], v[202:205], v[24:27]
	v_mfma_f32_16x16x32_bf16 v[12:15], v[128:131], v[210:213], v[12:15]
	v_mfma_f32_16x16x32_bf16 v[8:11], v[136:139], v[210:213], v[8:11]
	v_mfma_f32_16x16x32_bf16 v[60:63], v[132:135], v[178:181], v[60:63]
	v_mfma_f32_16x16x32_bf16 v[56:59], v[140:143], v[178:181], v[56:59]
	v_mfma_f32_16x16x32_bf16 v[44:47], v[132:135], v[198:201], v[44:47]
	v_mfma_f32_16x16x32_bf16 v[40:43], v[140:143], v[198:201], v[40:43]
	v_mfma_f32_16x16x32_bf16 v[28:31], v[132:135], v[206:209], v[28:31]
	v_mfma_f32_16x16x32_bf16 v[24:27], v[140:143], v[206:209], v[24:27]
	v_mfma_f32_16x16x32_bf16 v[12:15], v[132:135], v[214:217], v[12:15]
	v_mfma_f32_16x16x32_bf16 v[8:11], v[140:143], v[214:217], v[8:11]
	v_mfma_f32_16x16x32_bf16 v[52:55], v[144:147], v[174:177], v[52:55]
	v_mfma_f32_16x16x32_bf16 v[48:51], v[166:169], v[174:177], v[48:51]
	v_mfma_f32_16x16x32_bf16 v[36:39], v[144:147], v[194:197], v[36:39]
	v_mfma_f32_16x16x32_bf16 v[32:35], v[166:169], v[194:197], v[32:35]
	v_mfma_f32_16x16x32_bf16 v[20:23], v[144:147], v[202:205], v[20:23]
	v_mfma_f32_16x16x32_bf16 v[16:19], v[166:169], v[202:205], v[16:19]
	v_mfma_f32_16x16x32_bf16 v[4:7], v[144:147], v[210:213], v[4:7]
	v_mfma_f32_16x16x32_bf16 v[0:3], v[166:169], v[210:213], v[0:3]
	v_mfma_f32_16x16x32_bf16 v[52:55], v[148:151], v[178:181], v[52:55]
	v_mfma_f32_16x16x32_bf16 v[48:51], v[170:173], v[178:181], v[48:51]
	v_mfma_f32_16x16x32_bf16 v[36:39], v[148:151], v[198:201], v[36:39]
	v_mfma_f32_16x16x32_bf16 v[32:35], v[170:173], v[198:201], v[32:35]
	v_mfma_f32_16x16x32_bf16 v[20:23], v[148:151], v[206:209], v[20:23]
	v_mfma_f32_16x16x32_bf16 v[16:19], v[170:173], v[206:209], v[16:19]
	v_mfma_f32_16x16x32_bf16 v[4:7], v[148:151], v[214:217], v[4:7]
	v_mfma_f32_16x16x32_bf16 v[0:3], v[170:173], v[214:217], v[0:3]
	s_barrier
	s_add_i32 s63, s63, 2
	s_add_u32 s38, s38, 0x100
	s_addc_u32 s39, s39, 0
	s_add_u32 s61, s61, 0x100
	s_addc_u32 s62, s62, 0
	s_cmp_gt_u32 s63, 13
	s_cbranch_scc0 .LBB0_743
	s_and_b64 vcc, exec, s[18:19]
	s_cbranch_vccz .LBB0_746
	s_barrier

.LBB0_923:
	s_add_u32 s16, s72, 0x4880000
	s_addc_u32 s17, s73, 0
	s_lshl_b32 s5, s5, 5
	s_mov_b64 s[18:19], 0x80
	s_and_b32 s22, s5, 0x60
	s_add_i32 m0, s39, 0x18000
	v_lshl_add_u64 v[6:7], v[6:7], 0, s[18:19]
	s_lshl_b32 s21, s4, 13
	s_lshl_b32 s5, s22, 7
	s_waitcnt vmcnt(2)
	s_barrier
	global_load_lds_dwordx4 v[6:7], off
	v_lshl_add_u64 v[4:5], v[4:5], 0, s[18:19]
	s_add_i32 m0, s39, 0x1a000
	s_add_i32 s54, s39, 0x8000
	s_add_i32 s55, s39, 0xa000
	global_load_lds_dwordx4 v[4:5], off
	v_lshl_add_u64 v[0:1], v[0:1], 0, s[18:19]
	s_mov_b32 m0, s54
	s_add_u32 s24, s42, 0x100080
	global_load_lds_dwordx4 v[0:1], off
	v_lshl_add_u64 v[0:1], v[2:3], 0, s[18:19]
	s_mov_b32 m0, s55
	s_addc_u32 s25, s43, 0
	global_load_lds_dwordx4 v[0:1], off
	s_add_i32 m0, s39, 0x1c000
	v_lshl_add_u64 v[0:1], s[24:25], 0, v[154:155]
	global_load_lds_dwordx4 v[0:1], off
	v_lshl_add_u64 v[0:1], s[24:25], 0, v[158:159]
	s_add_i32 m0, s39, 0x1e000
	v_lshl_or_b32 v199, s4, 6, v191
	global_load_lds_dwordx4 v[0:1], off
	v_bfe_u32 v0, v192, 4, 2
	v_lshlrev_b32_e32 v1, 4, v0
	v_lshl_or_b32 v2, v191, 6, v1
	v_or_b32_e32 v1, v1, v190
	v_bitop3_b32 v200, s5, v1, v193 bitop3:0xf6
	v_cmp_eq_u32_e64 s[4:5], 0, v0
	v_lshl_or_b32 v201, v0, 3, s22
	v_lshlrev_b32_e32 v0, 10, v192
	v_and_b32_e32 v0, 0xe0000, v0
	v_lshlrev_b32_e32 v1, 13, v186
	v_or3_b32 v0, v184, v0, v1
	v_add_u32_e32 v160, v0, v185
	v_lshlrev_b32_e32 v0, 6, v8
	v_lshlrev_b32_e32 v3, 2, v191
	v_and_b32_e32 v0, 0x1e0000, v0
	v_and_b32_e32 v3, 32, v3
	s_waitcnt vmcnt(6)
	s_cmpk_lt_u32 s20, 0x100
	v_or3_b32 v0, v184, v0, v1
	v_bitop3_b32 v2, v2, s21, v3 bitop3:0xde
	s_cselect_b64 s[20:21], -1, 0
	v_add_u32_e32 v162, v0, v185
	s_add_i32 s58, 0, 0x10000
	s_add_i32 s59, 0, 0x14000
	v_mbcnt_lo_u32_b32 v0, -1, 0
	s_add_i32 s56, s3, -2
	s_ashr_i32 s57, s2, 31
	v_mov_b32_e32 v161, v155
	v_mov_b32_e32 v163, v155
	v_add_u32_e32 v202, s58, v200
	v_add_u32_e32 v203, s59, v200
	v_add_u32_e32 v204, 0, v2
	v_mbcnt_hi_u32_b32 v205, -1, v0
	v_mov_b64_e32 v[164:165], 0x1ff
	s_barrier
	s_waitcnt vmcnt(0)
	s_branch .LBB0_926

.LBB0_933:
	s_ashr_i32 s25, s24, 31
	s_lshl_b64 s[28:29], s[24:25], 21
	s_add_u32 s28, s46, s28
	s_addc_u32 s29, s47, s29
	s_and_b64 s[30:31], s[26:27], exec
	s_cselect_b32 s25, s29, s41
	s_cselect_b32 s37, s28, s40
	s_ashr_i32 s23, s22, 31
	s_lshl_b64 s[30:31], s[22:23], 21
	s_add_u32 s30, s48, s30
	s_addc_u32 s31, s49, s31
	s_and_b64 s[44:45], s[26:27], exec
	s_cselect_b32 s23, s31, s43
	s_cselect_b32 s61, s30, s42
	s_add_u32 s40, s40, 0x100080
	s_addc_u32 s41, s41, 0
	s_add_u32 s62, s42, 0x100
	v_mov_b32_e32 v0, 0
	s_addc_u32 s63, s43, 0
	s_mov_b32 s64, -2
	s_waitcnt lgkmcnt(0)
	v_mov_b32_e32 v1, v0
	v_mov_b32_e32 v2, v0
	v_mov_b32_e32 v3, v0
	v_mov_b32_e32 v4, v0
	v_mov_b32_e32 v5, v0
	v_mov_b32_e32 v6, v0
	v_mov_b32_e32 v7, v0
	v_mov_b32_e32 v16, v0
	v_mov_b32_e32 v17, v0
	v_mov_b32_e32 v18, v0
	v_mov_b32_e32 v19, v0
	v_mov_b32_e32 v20, v0
	v_mov_b32_e32 v21, v0
	v_mov_b32_e32 v22, v0
	v_mov_b32_e32 v23, v0
	v_mov_b32_e32 v32, v0
	v_mov_b32_e32 v33, v0
	v_mov_b32_e32 v34, v0
	v_mov_b32_e32 v35, v0
	v_mov_b32_e32 v36, v0
	v_mov_b32_e32 v37, v0
	v_mov_b32_e32 v38, v0
	v_mov_b32_e32 v39, v0
	v_mov_b32_e32 v48, v0
	v_mov_b32_e32 v49, v0
	v_mov_b32_e32 v50, v0
	v_mov_b32_e32 v51, v0
	v_mov_b32_e32 v52, v0
	v_mov_b32_e32 v53, v0
	v_mov_b32_e32 v54, v0
	v_mov_b32_e32 v55, v0
	v_mov_b32_e32 v8, v0
	v_mov_b32_e32 v9, v0
	v_mov_b32_e32 v10, v0
	v_mov_b32_e32 v11, v0
	v_mov_b32_e32 v12, v0
	v_mov_b32_e32 v13, v0
	v_mov_b32_e32 v14, v0
	v_mov_b32_e32 v15, v0
	v_mov_b32_e32 v24, v0
	v_mov_b32_e32 v25, v0
	v_mov_b32_e32 v26, v0
	v_mov_b32_e32 v27, v0
	v_mov_b32_e32 v28, v0
	v_mov_b32_e32 v29, v0
	v_mov_b32_e32 v30, v0
	v_mov_b32_e32 v31, v0
	v_mov_b32_e32 v40, v0
	v_mov_b32_e32 v41, v0
	v_mov_b32_e32 v42, v0
	v_mov_b32_e32 v43, v0
	v_mov_b32_e32 v44, v0
	v_mov_b32_e32 v45, v0
	v_mov_b32_e32 v46, v0
	v_mov_b32_e32 v47, v0
	v_mov_b32_e32 v56, v0
	v_mov_b32_e32 v57, v0
	v_mov_b32_e32 v58, v0
	v_mov_b32_e32 v59, v0
	v_mov_b32_e32 v60, v0
	v_mov_b32_e32 v61, v0
	v_mov_b32_e32 v62, v0
	v_mov_b32_e32 v63, v0
	v_mov_b32_e32 v64, v0
	v_mov_b32_e32 v65, v0
	v_mov_b32_e32 v66, v0
	v_mov_b32_e32 v67, v0
	v_mov_b32_e32 v68, v0
	v_mov_b32_e32 v69, v0
	v_mov_b32_e32 v70, v0
	v_mov_b32_e32 v71, v0
	v_mov_b32_e32 v80, v0
	v_mov_b32_e32 v81, v0
	v_mov_b32_e32 v82, v0
	v_mov_b32_e32 v83, v0
	v_mov_b32_e32 v84, v0
	v_mov_b32_e32 v85, v0
	v_mov_b32_e32 v86, v0
	v_mov_b32_e32 v87, v0
	v_mov_b32_e32 v96, v0
	v_mov_b32_e32 v97, v0
	v_mov_b32_e32 v98, v0
	v_mov_b32_e32 v99, v0
	v_mov_b32_e32 v100, v0
	v_mov_b32_e32 v101, v0
	v_mov_b32_e32 v102, v0
	v_mov_b32_e32 v103, v0
	v_mov_b32_e32 v112, v0
	v_mov_b32_e32 v113, v0
	v_mov_b32_e32 v114, v0
	v_mov_b32_e32 v115, v0
	v_mov_b32_e32 v116, v0
	v_mov_b32_e32 v117, v0
	v_mov_b32_e32 v118, v0
	v_mov_b32_e32 v119, v0
	v_mov_b32_e32 v72, v0
	v_mov_b32_e32 v73, v0
	v_mov_b32_e32 v74, v0
	v_mov_b32_e32 v75, v0
	v_mov_b32_e32 v76, v0
	v_mov_b32_e32 v77, v0
	v_mov_b32_e32 v78, v0
	v_mov_b32_e32 v79, v0
	v_mov_b32_e32 v88, v0
	v_mov_b32_e32 v89, v0
	v_mov_b32_e32 v90, v0
	v_mov_b32_e32 v91, v0
	v_mov_b32_e32 v92, v0
	v_mov_b32_e32 v93, v0
	v_mov_b32_e32 v94, v0
	v_mov_b32_e32 v95, v0
	v_mov_b32_e32 v104, v0
	v_mov_b32_e32 v105, v0
	v_mov_b32_e32 v106, v0
	v_mov_b32_e32 v107, v0
	v_mov_b32_e32 v108, v0
	v_mov_b32_e32 v109, v0
	v_mov_b32_e32 v110, v0
	v_mov_b32_e32 v111, v0
	v_mov_b32_e32 v120, v0
	v_mov_b32_e32 v121, v0
	v_mov_b32_e32 v122, v0
	v_mov_b32_e32 v123, v0
	v_mov_b32_e32 v124, v0
	v_mov_b32_e32 v125, v0
	v_mov_b32_e32 v126, v0
	v_mov_b32_e32 v127, v0
.LBB0_934:
	ds_read_b128 v[128:131], v202
	ds_read_b128 v[132:135], v202 offset:1024
	ds_read_b128 v[136:139], v202 offset:2048
	ds_read_b128 v[140:143], v202 offset:3072
	ds_read_b128 v[144:147], v203
	ds_read_b128 v[148:151], v203 offset:1024
	ds_read_b128 v[166:169], v203 offset:2048
	ds_read_b128 v[170:173], v203 offset:3072
	s_add_u32 s42, s40, 0xfff00080
	s_addc_u32 s43, s41, -1
	s_cmp_eq_u32 s64, 60
	s_cselect_b32 s45, s25, s43
	s_cselect_b32 s44, s37, s42
	s_cselect_b32 s43, s23, s63
	s_cselect_b32 s42, s61, s62
	v_lshl_add_u64 v[182:183], s[40:41], 0, v[160:161]
	s_add_i32 m0, s39, 0xc000
	ds_read_b128 v[174:177], v204
	ds_read_b128 v[178:181], v204 offset:1024
	ds_read_b128 v[206:209], v204 offset:2048
	ds_read_b128 v[210:213], v204 offset:3072
	ds_read_b128 v[214:217], v204 offset:4096
	ds_read_b128 v[218:221], v204 offset:5120
	ds_read_b128 v[222:225], v204 offset:6144
	ds_read_b128 v[226:229], v204 offset:7168
	global_load_lds_dwordx4 v[182:183], off
	v_lshl_add_u64 v[182:183], s[40:41], 0, v[162:163]
	s_add_i32 m0, s39, 0xe000
	s_nop 0
	global_load_lds_dwordx4 v[182:183], off
	s_cmp_eq_i32 s64, -2
	s_cbranch_scc1 .Lrxa_1_0
	s_waitcnt vmcnt(8)
.Lrxa_1_0:
	s_waitcnt lgkmcnt(0)
	s_barrier
	s_waitcnt lgkmcnt(0)
	v_mfma_f32_16x16x32_bf16 v[124:127], v[128:131], v[174:177], v[124:127]
	v_mfma_f32_16x16x32_bf16 v[120:123], v[136:139], v[174:177], v[120:123]
	v_mfma_f32_16x16x32_bf16 v[108:111], v[128:131], v[206:209], v[108:111]
	v_mfma_f32_16x16x32_bf16 v[104:107], v[136:139], v[206:209], v[104:107]
	v_mfma_f32_16x16x32_bf16 v[92:95], v[128:131], v[214:217], v[92:95]
	v_mfma_f32_16x16x32_bf16 v[88:91], v[136:139], v[214:217], v[88:91]
	v_mfma_f32_16x16x32_bf16 v[76:79], v[128:131], v[222:225], v[76:79]
	v_mfma_f32_16x16x32_bf16 v[72:75], v[136:139], v[222:225], v[72:75]
	v_mfma_f32_16x16x32_bf16 v[124:127], v[132:135], v[178:181], v[124:127]
	v_mfma_f32_16x16x32_bf16 v[120:123], v[140:143], v[178:181], v[120:123]
	v_mfma_f32_16x16x32_bf16 v[108:111], v[132:135], v[210:213], v[108:111]
	v_mfma_f32_16x16x32_bf16 v[104:107], v[140:143], v[210:213], v[104:107]
	v_mfma_f32_16x16x32_bf16 v[92:95], v[132:135], v[218:221], v[92:95]
	v_mfma_f32_16x16x32_bf16 v[88:91], v[140:143], v[218:221], v[88:91]
	v_mfma_f32_16x16x32_bf16 v[76:79], v[132:135], v[226:229], v[76:79]
	v_mfma_f32_16x16x32_bf16 v[72:75], v[140:143], v[226:229], v[72:75]
	v_mfma_f32_16x16x32_bf16 v[116:119], v[144:147], v[174:177], v[116:119]
	v_mfma_f32_16x16x32_bf16 v[112:115], v[166:169], v[174:177], v[112:115]
	v_mfma_f32_16x16x32_bf16 v[100:103], v[144:147], v[206:209], v[100:103]
	v_mfma_f32_16x16x32_bf16 v[96:99], v[166:169], v[206:209], v[96:99]
	v_mfma_f32_16x16x32_bf16 v[84:87], v[144:147], v[214:217], v[84:87]
	v_mfma_f32_16x16x32_bf16 v[80:83], v[166:169], v[214:217], v[80:83]
	v_mfma_f32_16x16x32_bf16 v[68:71], v[144:147], v[222:225], v[68:71]
	v_mfma_f32_16x16x32_bf16 v[64:67], v[166:169], v[222:225], v[64:67]
	v_mfma_f32_16x16x32_bf16 v[116:119], v[148:151], v[178:181], v[116:119]
	v_mfma_f32_16x16x32_bf16 v[112:115], v[170:173], v[178:181], v[112:115]
	v_mfma_f32_16x16x32_bf16 v[100:103], v[148:151], v[210:213], v[100:103]
	v_mfma_f32_16x16x32_bf16 v[96:99], v[170:173], v[210:213], v[96:99]
	v_mfma_f32_16x16x32_bf16 v[84:87], v[148:151], v[218:221], v[84:87]
	v_mfma_f32_16x16x32_bf16 v[80:83], v[170:173], v[218:221], v[80:83]
	v_mfma_f32_16x16x32_bf16 v[68:71], v[148:151], v[226:229], v[68:71]
	v_mfma_f32_16x16x32_bf16 v[64:67], v[170:173], v[226:229], v[64:67]
	s_barrier
	s_add_i32 s65, s58, s50
	v_lshl_add_u64 v[182:183], s[42:43], 0, v[154:155]
	s_mov_b32 m0, s65
	ds_read_b128 v[174:177], v204 offset:16384
	ds_read_b128 v[178:181], v204 offset:17408
	ds_read_b128 v[206:209], v204 offset:18432
	ds_read_b128 v[210:213], v204 offset:19456
	ds_read_b128 v[214:217], v204 offset:20480
	ds_read_b128 v[218:221], v204 offset:21504
	ds_read_b128 v[222:225], v204 offset:22528
	ds_read_b128 v[226:229], v204 offset:23552
	global_load_lds_dwordx4 v[182:183], off
	s_add_i32 m0, s65, 0x2000
	s_add_u32 s66, s42, 0x100000
	v_lshl_add_u64 v[230:231], s[42:43], 0, v[158:159]
	s_addc_u32 s67, s43, 0
	s_add_i32 s65, s59, s50
	global_load_lds_dwordx4 v[230:231], off
	v_lshl_add_u64 v[232:233], s[66:67], 0, v[154:155]
	s_mov_b32 m0, s65
	v_lshl_add_u64 v[234:235], s[44:45], 0, v[156:157]
	global_load_lds_dwordx4 v[232:233], off
	v_lshl_add_u64 v[232:233], s[66:67], 0, v[158:159]
	s_add_i32 m0, s65, 0x2000
	s_nop 0
	global_load_lds_dwordx4 v[232:233], off
	v_lshl_add_u64 v[232:233], s[44:45], 0, v[152:153]
	s_mov_b32 m0, s39
	s_nop 0
	global_load_lds_dwordx4 v[232:233], off
	s_mov_b32 m0, s51
	s_nop 0
	global_load_lds_dwordx4 v[234:235], off
	s_cmp_eq_i32 s64, -2
	s_cbranch_scc1 .Lrxa_1_1
	s_waitcnt vmcnt(8)
.Lrxa_1_1:
	s_waitcnt lgkmcnt(0)
	s_barrier
	s_waitcnt lgkmcnt(0)
	v_mfma_f32_16x16x32_bf16 v[60:63], v[128:131], v[174:177], v[60:63]
	v_mfma_f32_16x16x32_bf16 v[56:59], v[136:139], v[174:177], v[56:59]
	v_mfma_f32_16x16x32_bf16 v[44:47], v[128:131], v[206:209], v[44:47]
	v_mfma_f32_16x16x32_bf16 v[40:43], v[136:139], v[206:209], v[40:43]
	v_mfma_f32_16x16x32_bf16 v[28:31], v[128:131], v[214:217], v[28:31]
	v_mfma_f32_16x16x32_bf16 v[24:27], v[136:139], v[214:217], v[24:27]
	v_mfma_f32_16x16x32_bf16 v[12:15], v[128:131], v[222:225], v[12:15]
	v_mfma_f32_16x16x32_bf16 v[8:11], v[136:139], v[222:225], v[8:11]
	v_mfma_f32_16x16x32_bf16 v[60:63], v[132:135], v[178:181], v[60:63]
	v_mfma_f32_16x16x32_bf16 v[56:59], v[140:143], v[178:181], v[56:59]
	v_mfma_f32_16x16x32_bf16 v[44:47], v[132:135], v[210:213], v[44:47]
	v_mfma_f32_16x16x32_bf16 v[40:43], v[140:143], v[210:213], v[40:43]
	v_mfma_f32_16x16x32_bf16 v[28:31], v[132:135], v[218:221], v[28:31]
	v_mfma_f32_16x16x32_bf16 v[24:27], v[140:143], v[218:221], v[24:27]
	v_mfma_f32_16x16x32_bf16 v[12:15], v[132:135], v[226:229], v[12:15]
	v_mfma_f32_16x16x32_bf16 v[8:11], v[140:143], v[226:229], v[8:11]
	v_mfma_f32_16x16x32_bf16 v[52:55], v[144:147], v[174:177], v[52:55]
	v_mfma_f32_16x16x32_bf16 v[48:51], v[166:169], v[174:177], v[48:51]
	v_mfma_f32_16x16x32_bf16 v[36:39], v[144:147], v[206:209], v[36:39]
	v_mfma_f32_16x16x32_bf16 v[32:35], v[166:169], v[206:209], v[32:35]
	v_mfma_f32_16x16x32_bf16 v[20:23], v[144:147], v[214:217], v[20:23]
	v_mfma_f32_16x16x32_bf16 v[16:19], v[166:169], v[214:217], v[16:19]
	v_mfma_f32_16x16x32_bf16 v[4:7], v[144:147], v[222:225], v[4:7]
	v_mfma_f32_16x16x32_bf16 v[0:3], v[166:169], v[222:225], v[0:3]
	v_mfma_f32_16x16x32_bf16 v[52:55], v[148:151], v[178:181], v[52:55]
	v_mfma_f32_16x16x32_bf16 v[48:51], v[170:173], v[178:181], v[48:51]
	v_mfma_f32_16x16x32_bf16 v[36:39], v[148:151], v[210:213], v[36:39]
	v_mfma_f32_16x16x32_bf16 v[32:35], v[170:173], v[210:213], v[32:35]
	v_mfma_f32_16x16x32_bf16 v[20:23], v[148:151], v[218:221], v[20:23]
	v_mfma_f32_16x16x32_bf16 v[16:19], v[170:173], v[218:221], v[16:19]
	v_mfma_f32_16x16x32_bf16 v[4:7], v[148:151], v[226:229], v[4:7]
	v_mfma_f32_16x16x32_bf16 v[0:3], v[170:173], v[226:229], v[0:3]
	s_barrier
	s_add_i32 s65, 0, 0x18000
	s_add_i32 s66, 0, 0x1c000
	v_add_u32_e32 v140, s65, v200
	v_add_u32_e32 v170, s66, v200
	ds_read_b128 v[128:131], v140
	ds_read_b128 v[132:135], v140 offset:1024
	ds_read_b128 v[136:139], v140 offset:2048
	ds_read_b128 v[140:143], v140 offset:3072
	ds_read_b128 v[144:147], v170
	ds_read_b128 v[148:151], v170 offset:1024
	ds_read_b128 v[166:169], v170 offset:2048
	ds_read_b128 v[170:173], v170 offset:3072
	s_add_u32 s44, s44, 0x100000
	s_addc_u32 s45, s45, 0
	s_mov_b32 m0, s52
	v_lshl_add_u64 v[236:237], s[44:45], 0, v[152:153]
	ds_read_b128 v[174:177], v204 offset:32768
	ds_read_b128 v[178:181], v204 offset:33792
	ds_read_b128 v[206:209], v204 offset:34816
	ds_read_b128 v[210:213], v204 offset:35840
	ds_read_b128 v[214:217], v204 offset:36864
	ds_read_b128 v[218:221], v204 offset:37888
	ds_read_b128 v[222:225], v204 offset:38912
	ds_read_b128 v[226:229], v204 offset:39936
	global_load_lds_dwordx4 v[236:237], off
	v_lshl_add_u64 v[236:237], s[44:45], 0, v[156:157]
	s_mov_b32 m0, s53
	s_nop 0
	global_load_lds_dwordx4 v[236:237], off
	s_waitcnt vmcnt(8)
	s_waitcnt lgkmcnt(0)
	s_barrier
	s_waitcnt lgkmcnt(0)
	v_mfma_f32_16x16x32_bf16 v[124:127], v[128:131], v[174:177], v[124:127]
	v_mfma_f32_16x16x32_bf16 v[120:123], v[136:139], v[174:177], v[120:123]
	v_mfma_f32_16x16x32_bf16 v[108:111], v[128:131], v[206:209], v[108:111]
	v_mfma_f32_16x16x32_bf16 v[104:107], v[136:139], v[206:209], v[104:107]
	v_mfma_f32_16x16x32_bf16 v[92:95], v[128:131], v[214:217], v[92:95]
	v_mfma_f32_16x16x32_bf16 v[88:91], v[136:139], v[214:217], v[88:91]
	v_mfma_f32_16x16x32_bf16 v[76:79], v[128:131], v[222:225], v[76:79]
	v_mfma_f32_16x16x32_bf16 v[72:75], v[136:139], v[222:225], v[72:75]
	v_mfma_f32_16x16x32_bf16 v[124:127], v[132:135], v[178:181], v[124:127]
	v_mfma_f32_16x16x32_bf16 v[120:123], v[140:143], v[178:181], v[120:123]
	v_mfma_f32_16x16x32_bf16 v[108:111], v[132:135], v[210:213], v[108:111]
	v_mfma_f32_16x16x32_bf16 v[104:107], v[140:143], v[210:213], v[104:107]
	v_mfma_f32_16x16x32_bf16 v[92:95], v[132:135], v[218:221], v[92:95]
	v_mfma_f32_16x16x32_bf16 v[88:91], v[140:143], v[218:221], v[88:91]
	v_mfma_f32_16x16x32_bf16 v[76:79], v[132:135], v[226:229], v[76:79]
	v_mfma_f32_16x16x32_bf16 v[72:75], v[140:143], v[226:229], v[72:75]
	v_mfma_f32_16x16x32_bf16 v[116:119], v[144:147], v[174:177], v[116:119]
	v_mfma_f32_16x16x32_bf16 v[112:115], v[166:169], v[174:177], v[112:115]
	v_mfma_f32_16x16x32_bf16 v[100:103], v[144:147], v[206:209], v[100:103]
	v_mfma_f32_16x16x32_bf16 v[96:99], v[166:169], v[206:209], v[96:99]
	v_mfma_f32_16x16x32_bf16 v[84:87], v[144:147], v[214:217], v[84:87]
	v_mfma_f32_16x16x32_bf16 v[80:83], v[166:169], v[214:217], v[80:83]
	v_mfma_f32_16x16x32_bf16 v[68:71], v[144:147], v[222:225], v[68:71]
	v_mfma_f32_16x16x32_bf16 v[64:67], v[166:169], v[222:225], v[64:67]
	v_mfma_f32_16x16x32_bf16 v[116:119], v[148:151], v[178:181], v[116:119]
	v_mfma_f32_16x16x32_bf16 v[112:115], v[170:173], v[178:181], v[112:115]
	v_mfma_f32_16x16x32_bf16 v[100:103], v[148:151], v[210:213], v[100:103]
	v_mfma_f32_16x16x32_bf16 v[96:99], v[170:173], v[210:213], v[96:99]
	v_mfma_f32_16x16x32_bf16 v[84:87], v[148:151], v[218:221], v[84:87]
	v_mfma_f32_16x16x32_bf16 v[80:83], v[170:173], v[218:221], v[80:83]
	v_mfma_f32_16x16x32_bf16 v[68:71], v[148:151], v[226:229], v[68:71]
	v_mfma_f32_16x16x32_bf16 v[64:67], v[170:173], v[226:229], v[64:67]
	s_barrier
	s_add_i32 s44, s65, s50
	v_lshl_add_u64 v[182:183], v[182:183], 0, s[18:19]
	s_mov_b32 m0, s44
	ds_read_b128 v[174:177], v204 offset:49152
	ds_read_b128 v[178:181], v204 offset:50176
	ds_read_b128 v[206:209], v204 offset:51200
	ds_read_b128 v[210:213], v204 offset:52224
	ds_read_b128 v[214:217], v204 offset:53248
	ds_read_b128 v[218:221], v204 offset:54272
	ds_read_b128 v[222:225], v204 offset:55296
	ds_read_b128 v[226:229], v204 offset:56320
	global_load_lds_dwordx4 v[182:183], off
	s_add_i32 m0, s44, 0x2000
	s_add_u32 s42, s42, 0x100080
	v_lshl_add_u64 v[182:183], v[230:231], 0, s[18:19]
	s_addc_u32 s43, s43, 0
	s_add_i32 s44, s66, s50
	global_load_lds_dwordx4 v[182:183], off
	v_lshl_add_u64 v[182:183], s[42:43], 0, v[154:155]
	s_mov_b32 m0, s44
	s_nop 0
	global_load_lds_dwordx4 v[182:183], off
	v_lshl_add_u64 v[182:183], s[42:43], 0, v[158:159]
	s_add_i32 m0, s44, 0x2000
	s_nop 0
	global_load_lds_dwordx4 v[182:183], off
	v_lshl_add_u64 v[182:183], v[232:233], 0, s[18:19]
	s_mov_b32 m0, s54
	s_nop 0
	global_load_lds_dwordx4 v[182:183], off
	v_lshl_add_u64 v[182:183], v[234:235], 0, s[18:19]
	s_mov_b32 m0, s55
	s_nop 0
	global_load_lds_dwordx4 v[182:183], off
	s_waitcnt vmcnt(8)
	s_waitcnt lgkmcnt(0)
	s_barrier
	s_waitcnt lgkmcnt(0)
	v_mfma_f32_16x16x32_bf16 v[60:63], v[128:131], v[174:177], v[60:63]
	v_mfma_f32_16x16x32_bf16 v[56:59], v[136:139], v[174:177], v[56:59]
	v_mfma_f32_16x16x32_bf16 v[44:47], v[128:131], v[206:209], v[44:47]
	v_mfma_f32_16x16x32_bf16 v[40:43], v[136:139], v[206:209], v[40:43]
	v_mfma_f32_16x16x32_bf16 v[28:31], v[128:131], v[214:217], v[28:31]
	v_mfma_f32_16x16x32_bf16 v[24:27], v[136:139], v[214:217], v[24:27]
	v_mfma_f32_16x16x32_bf16 v[12:15], v[128:131], v[222:225], v[12:15]
	v_mfma_f32_16x16x32_bf16 v[8:11], v[136:139], v[222:225], v[8:11]
	v_mfma_f32_16x16x32_bf16 v[60:63], v[132:135], v[178:181], v[60:63]
	v_mfma_f32_16x16x32_bf16 v[56:59], v[140:143], v[178:181], v[56:59]
	v_mfma_f32_16x16x32_bf16 v[44:47], v[132:135], v[210:213], v[44:47]
	v_mfma_f32_16x16x32_bf16 v[40:43], v[140:143], v[210:213], v[40:43]
	v_mfma_f32_16x16x32_bf16 v[28:31], v[132:135], v[218:221], v[28:31]
	v_mfma_f32_16x16x32_bf16 v[24:27], v[140:143], v[218:221], v[24:27]
	v_mfma_f32_16x16x32_bf16 v[12:15], v[132:135], v[226:229], v[12:15]
	v_mfma_f32_16x16x32_bf16 v[8:11], v[140:143], v[226:229], v[8:11]
	v_mfma_f32_16x16x32_bf16 v[52:55], v[144:147], v[174:177], v[52:55]
	v_mfma_f32_16x16x32_bf16 v[48:51], v[166:169], v[174:177], v[48:51]
	v_mfma_f32_16x16x32_bf16 v[36:39], v[144:147], v[206:209], v[36:39]
	v_mfma_f32_16x16x32_bf16 v[32:35], v[166:169], v[206:209], v[32:35]
	v_mfma_f32_16x16x32_bf16 v[20:23], v[144:147], v[214:217], v[20:23]
	v_mfma_f32_16x16x32_bf16 v[16:19], v[166:169], v[214:217], v[16:19]
	v_mfma_f32_16x16x32_bf16 v[4:7], v[144:147], v[222:225], v[4:7]
	v_mfma_f32_16x16x32_bf16 v[0:3], v[166:169], v[222:225], v[0:3]
	v_mfma_f32_16x16x32_bf16 v[52:55], v[148:151], v[178:181], v[52:55]
	v_mfma_f32_16x16x32_bf16 v[48:51], v[170:173], v[178:181], v[48:51]
	v_mfma_f32_16x16x32_bf16 v[36:39], v[148:151], v[210:213], v[36:39]
	v_mfma_f32_16x16x32_bf16 v[32:35], v[170:173], v[210:213], v[32:35]
	v_mfma_f32_16x16x32_bf16 v[20:23], v[148:151], v[218:221], v[20:23]
	v_mfma_f32_16x16x32_bf16 v[16:19], v[170:173], v[218:221], v[16:19]
	v_mfma_f32_16x16x32_bf16 v[4:7], v[148:151], v[226:229], v[4:7]
	v_mfma_f32_16x16x32_bf16 v[0:3], v[170:173], v[226:229], v[0:3]
	s_barrier
	s_add_i32 s64, s64, 2
	s_add_u32 s40, s40, 0x100
	s_addc_u32 s41, s41, 0
	s_add_u32 s62, s62, 0x100
	s_addc_u32 s63, s63, 0
	s_cmp_gt_u32 s64, 61
	s_cbranch_scc0 .LBB0_934
	s_and_b64 vcc, exec, s[20:21]
	s_cbranch_vccz .LBB0_937
	s_barrier

.LBB0_1369:
	s_add_u32 s16, s72, 0x48e0000
	s_addc_u32 s17, s73, 0
	s_lshl_b32 s5, s5, 5
	s_mov_b64 s[18:19], 0x80
	s_and_b32 s22, s5, 0x60
	s_add_i32 m0, s39, 0x18000
	v_lshl_add_u64 v[6:7], v[6:7], 0, s[18:19]
	s_lshl_b32 s21, s4, 13
	s_lshl_b32 s5, s22, 7
	s_waitcnt vmcnt(2)
	s_barrier
	global_load_lds_dwordx4 v[6:7], off
	v_lshl_add_u64 v[4:5], v[4:5], 0, s[18:19]
	s_add_i32 m0, s39, 0x1a000
	s_add_i32 s54, s39, 0x8000
	s_add_i32 s55, s39, 0xa000
	global_load_lds_dwordx4 v[4:5], off
	v_lshl_add_u64 v[0:1], v[0:1], 0, s[18:19]
	s_mov_b32 m0, s54
	s_add_u32 s24, s42, 0x100080
	global_load_lds_dwordx4 v[0:1], off
	v_lshl_add_u64 v[0:1], v[2:3], 0, s[18:19]
	s_mov_b32 m0, s55
	s_addc_u32 s25, s43, 0
	global_load_lds_dwordx4 v[0:1], off
	s_add_i32 m0, s39, 0x1c000
	v_lshl_add_u64 v[0:1], s[24:25], 0, v[154:155]
	global_load_lds_dwordx4 v[0:1], off
	v_lshl_add_u64 v[0:1], s[24:25], 0, v[158:159]
	s_add_i32 m0, s39, 0x1e000
	v_lshl_or_b32 v199, s4, 6, v191
	global_load_lds_dwordx4 v[0:1], off
	v_bfe_u32 v0, v192, 4, 2
	v_lshlrev_b32_e32 v1, 4, v0
	v_lshl_or_b32 v2, v191, 6, v1
	v_or_b32_e32 v1, v1, v190
	v_bitop3_b32 v200, s5, v1, v193 bitop3:0xf6
	v_cmp_eq_u32_e64 s[4:5], 0, v0
	v_lshl_or_b32 v201, v0, 3, s22
	v_lshlrev_b32_e32 v0, 10, v192
	v_and_b32_e32 v0, 0xe0000, v0
	v_lshlrev_b32_e32 v1, 13, v186
	v_or3_b32 v0, v184, v0, v1
	v_add_u32_e32 v160, v0, v185
	v_lshlrev_b32_e32 v0, 6, v8
	v_lshlrev_b32_e32 v3, 2, v191
	v_and_b32_e32 v0, 0x1e0000, v0
	v_and_b32_e32 v3, 32, v3
	s_waitcnt vmcnt(6)
	s_cmpk_lt_u32 s20, 0x100
	v_or3_b32 v0, v184, v0, v1
	v_bitop3_b32 v2, v2, s21, v3 bitop3:0xde
	s_cselect_b64 s[20:21], -1, 0
	v_add_u32_e32 v162, v0, v185
	s_add_i32 s58, 0, 0x10000
	s_add_i32 s59, 0, 0x14000
	v_mbcnt_lo_u32_b32 v0, -1, 0
	s_add_i32 s56, s3, -2
	s_ashr_i32 s57, s2, 31
	v_mov_b32_e32 v161, v155
	v_mov_b32_e32 v163, v155
	v_add_u32_e32 v202, s58, v200
	v_add_u32_e32 v203, s59, v200
	v_add_u32_e32 v204, 0, v2
	v_mbcnt_hi_u32_b32 v205, -1, v0
	v_mov_b64_e32 v[164:165], 0x1ff
	s_barrier
	s_waitcnt vmcnt(0)
	s_branch .LBB0_1372
